# attn_sample_unit K/V cache staging: all 16 row-piece loads issued up front with counted waits (were 8 serial load->wait->convert->store blocks)
# speedup vs baseline: 1.0036x; 1.0003x over previous
.LBB0_624:
	s_add_i32 s10, s25, s22
	s_waitcnt vmcnt(0) lgkmcnt(0)
	s_barrier
	s_ashr_i32 s11, s10, 31
	v_ashrrev_i32_e32 v12, 5, v137
	s_lshl_b64 s[10:11], s[10:11], 7
	v_ashrrev_i32_e32 v13, 31, v12
	v_lshlrev_b32_e32 v14, 2, v137
	v_lshl_add_u64 v[4:5], s[10:11], 0, v[12:13]
	v_and_b32_e32 v1, 0x7c, v14
	v_lshlrev_b64 v[8:9], 9, v[4:5]
	v_readlane_b32 s40, v254, 33
	v_lshl_or_b32 v8, v1, 2, v8
	v_readlane_b32 s44, v254, 37
	v_readlane_b32 s45, v254, 38
	v_readlane_b32 s46, v254, 39
	v_readlane_b32 s47, v254, 40
	v_lshl_add_u64 v[108:109], s[44:45], 0, v[8:9]
	v_lshl_add_u64 v[110:111], s[46:47], 0, v[8:9]
	s_mov_b32 s100, 0x2000
	s_mov_b32 s101, 0
	v_mov_b32_e32 v112, v12
	global_load_dwordx4 v[44:47], v[108:109], off
	global_load_dwordx4 v[48:51], v[110:111], off
	v_lshl_add_u64 v[108:109], v[108:109], 0, s[100:101]
	v_lshl_add_u64 v[110:111], v[110:111], 0, s[100:101]
	global_load_dwordx4 v[52:55], v[108:109], off
	global_load_dwordx4 v[56:59], v[110:111], off
	v_lshl_add_u64 v[108:109], v[108:109], 0, s[100:101]
	v_lshl_add_u64 v[110:111], v[110:111], 0, s[100:101]
	global_load_dwordx4 v[60:63], v[108:109], off
	global_load_dwordx4 v[64:67], v[110:111], off
	v_lshl_add_u64 v[108:109], v[108:109], 0, s[100:101]
	v_lshl_add_u64 v[110:111], v[110:111], 0, s[100:101]
	global_load_dwordx4 v[68:71], v[108:109], off
	global_load_dwordx4 v[72:75], v[110:111], off
	v_lshl_add_u64 v[108:109], v[108:109], 0, s[100:101]
	v_lshl_add_u64 v[110:111], v[110:111], 0, s[100:101]
	global_load_dwordx4 v[76:79], v[108:109], off
	global_load_dwordx4 v[80:83], v[110:111], off
	v_lshl_add_u64 v[108:109], v[108:109], 0, s[100:101]
	v_lshl_add_u64 v[110:111], v[110:111], 0, s[100:101]
	global_load_dwordx4 v[84:87], v[108:109], off
	global_load_dwordx4 v[88:91], v[110:111], off
	v_lshl_add_u64 v[108:109], v[108:109], 0, s[100:101]
	v_lshl_add_u64 v[110:111], v[110:111], 0, s[100:101]
	global_load_dwordx4 v[92:95], v[108:109], off
	global_load_dwordx4 v[96:99], v[110:111], off
	v_lshl_add_u64 v[108:109], v[108:109], 0, s[100:101]
	v_lshl_add_u64 v[110:111], v[110:111], 0, s[100:101]
	global_load_dwordx4 v[100:103], v[108:109], off
	global_load_dwordx4 v[104:107], v[110:111], off
	v_lshl_add_u32 v0, v1, 1, 0
	v_readfirstlane_b32 s8, v137
	v_readlane_b32 s41, v254, 34
	v_readlane_b32 s42, v254, 35
	v_readlane_b32 s43, v254, 36
	v_readlane_b32 s48, v254, 41
	v_readlane_b32 s49, v254, 42
	v_readlane_b32 s50, v254, 43
	v_readlane_b32 s51, v254, 44
	v_readlane_b32 s52, v254, 45
	v_readlane_b32 s53, v254, 46
	v_readlane_b32 s54, v254, 47
	v_readlane_b32 s55, v254, 48
	v_add_u32_e32 v12, 0, v112
	v_mad_u64_u32 v[18:19], s[12:13], v12, s96, v[0:1]
	v_cmp_lt_i32_e32 vcc, 3, v12
	s_waitcnt vmcnt(15)
	v_cvt_pk_bf16_f32 v16, v44, v45
	v_cvt_pk_bf16_f32 v17, v46, v47
	ds_write_b64 v18, v[16:17]
	s_waitcnt vmcnt(14)
	v_cvt_pk_bf16_f32 v16, v48, v49
	v_cvt_pk_bf16_f32 v17, v50, v51
	ds_write_b64 v18, v[16:17] offset:34848
	s_and_saveexec_b64 s[16:17], vcc
	s_cbranch_execz .Lsattn_0
	v_add_u32_e32 v2, -4, v12
	v_lshl_add_u64 v[12:13], s[10:11], 0, v[2:3]
	v_lshlrev_b64 v[12:13], 9, v[12:13]
	v_lshl_or_b32 v12, v1, 2, v12
	v_lshl_add_u64 v[16:17], s[4:5], 0, v[12:13]
	global_store_dwordx4 v[16:17], v[44:47], off
	s_nop 1
	v_lshl_add_u64 v[4:5], s[6:7], 0, v[12:13]
	global_store_dwordx4 v[4:5], v[48:51], off
.Lsattn_0:
	s_or_b64 exec, exec, s[16:17]
	v_add_u32_e32 v12, 16, v112
	v_mad_u64_u32 v[18:19], s[12:13], v12, s96, v[0:1]
	v_cmp_lt_i32_e32 vcc, 3, v12
	s_waitcnt vmcnt(13)
	v_cvt_pk_bf16_f32 v16, v52, v53
	v_cvt_pk_bf16_f32 v17, v54, v55
	ds_write_b64 v18, v[16:17]
	s_waitcnt vmcnt(12)
	v_cvt_pk_bf16_f32 v16, v56, v57
	v_cvt_pk_bf16_f32 v17, v58, v59
	ds_write_b64 v18, v[16:17] offset:34848
	s_and_saveexec_b64 s[16:17], vcc
	s_cbranch_execz .Lsattn_1
	v_add_u32_e32 v2, -4, v12
	v_lshl_add_u64 v[12:13], s[10:11], 0, v[2:3]
	v_lshlrev_b64 v[12:13], 9, v[12:13]
	v_lshl_or_b32 v12, v1, 2, v12
	v_lshl_add_u64 v[16:17], s[4:5], 0, v[12:13]
	global_store_dwordx4 v[16:17], v[52:55], off
	s_nop 1
	v_lshl_add_u64 v[4:5], s[6:7], 0, v[12:13]
	global_store_dwordx4 v[4:5], v[56:59], off
.Lsattn_1:
	s_or_b64 exec, exec, s[16:17]
	v_add_u32_e32 v12, 32, v112
	v_mad_u64_u32 v[18:19], s[12:13], v12, s96, v[0:1]
	v_cmp_lt_i32_e32 vcc, 3, v12
	s_waitcnt vmcnt(11)
	v_cvt_pk_bf16_f32 v16, v60, v61
	v_cvt_pk_bf16_f32 v17, v62, v63
	ds_write_b64 v18, v[16:17]
	s_waitcnt vmcnt(10)
	v_cvt_pk_bf16_f32 v16, v64, v65
	v_cvt_pk_bf16_f32 v17, v66, v67
	ds_write_b64 v18, v[16:17] offset:34848
	s_and_saveexec_b64 s[16:17], vcc
	s_cbranch_execz .Lsattn_2
	v_add_u32_e32 v2, -4, v12
	v_lshl_add_u64 v[12:13], s[10:11], 0, v[2:3]
	v_lshlrev_b64 v[12:13], 9, v[12:13]
	v_lshl_or_b32 v12, v1, 2, v12
	v_lshl_add_u64 v[16:17], s[4:5], 0, v[12:13]
	global_store_dwordx4 v[16:17], v[60:63], off
	s_nop 1
	v_lshl_add_u64 v[4:5], s[6:7], 0, v[12:13]
	global_store_dwordx4 v[4:5], v[64:67], off
.Lsattn_2:
	s_or_b64 exec, exec, s[16:17]
	v_add_u32_e32 v12, 48, v112
	v_mad_u64_u32 v[18:19], s[12:13], v12, s96, v[0:1]
	v_cmp_lt_i32_e32 vcc, 3, v12
	s_waitcnt vmcnt(9)
	v_cvt_pk_bf16_f32 v16, v68, v69
	v_cvt_pk_bf16_f32 v17, v70, v71
	ds_write_b64 v18, v[16:17]
	s_waitcnt vmcnt(8)
	v_cvt_pk_bf16_f32 v16, v72, v73
	v_cvt_pk_bf16_f32 v17, v74, v75
	ds_write_b64 v18, v[16:17] offset:34848
	s_and_saveexec_b64 s[16:17], vcc
	s_cbranch_execz .Lsattn_3
	v_add_u32_e32 v2, -4, v12
	v_lshl_add_u64 v[12:13], s[10:11], 0, v[2:3]
	v_lshlrev_b64 v[12:13], 9, v[12:13]
	v_lshl_or_b32 v12, v1, 2, v12
	v_lshl_add_u64 v[16:17], s[4:5], 0, v[12:13]
	global_store_dwordx4 v[16:17], v[68:71], off
	s_nop 1
	v_lshl_add_u64 v[4:5], s[6:7], 0, v[12:13]
	global_store_dwordx4 v[4:5], v[72:75], off
.Lsattn_3:
	s_or_b64 exec, exec, s[16:17]
	v_add_u32_e32 v12, 64, v112
	v_mad_u64_u32 v[18:19], s[12:13], v12, s96, v[0:1]
	v_cmp_lt_i32_e32 vcc, 3, v12
	s_waitcnt vmcnt(7)
	v_cvt_pk_bf16_f32 v16, v76, v77
	v_cvt_pk_bf16_f32 v17, v78, v79
	ds_write_b64 v18, v[16:17]
	s_waitcnt vmcnt(6)
	v_cvt_pk_bf16_f32 v16, v80, v81
	v_cvt_pk_bf16_f32 v17, v82, v83
	ds_write_b64 v18, v[16:17] offset:34848
	s_and_saveexec_b64 s[16:17], vcc
	s_cbranch_execz .Lsattn_4
	v_add_u32_e32 v2, -4, v12
	v_lshl_add_u64 v[12:13], s[10:11], 0, v[2:3]
	v_lshlrev_b64 v[12:13], 9, v[12:13]
	v_lshl_or_b32 v12, v1, 2, v12
	v_lshl_add_u64 v[16:17], s[4:5], 0, v[12:13]
	global_store_dwordx4 v[16:17], v[76:79], off
	s_nop 1
	v_lshl_add_u64 v[4:5], s[6:7], 0, v[12:13]
	global_store_dwordx4 v[4:5], v[80:83], off
.Lsattn_4:
	s_or_b64 exec, exec, s[16:17]
	v_add_u32_e32 v12, 80, v112
	v_mad_u64_u32 v[18:19], s[12:13], v12, s96, v[0:1]
	v_cmp_lt_i32_e32 vcc, 3, v12
	s_waitcnt vmcnt(5)
	v_cvt_pk_bf16_f32 v16, v84, v85
	v_cvt_pk_bf16_f32 v17, v86, v87
	ds_write_b64 v18, v[16:17]
	s_waitcnt vmcnt(4)
	v_cvt_pk_bf16_f32 v16, v88, v89
	v_cvt_pk_bf16_f32 v17, v90, v91
	ds_write_b64 v18, v[16:17] offset:34848
	s_and_saveexec_b64 s[16:17], vcc
	s_cbranch_execz .Lsattn_5
	v_add_u32_e32 v2, -4, v12
	v_lshl_add_u64 v[12:13], s[10:11], 0, v[2:3]
	v_lshlrev_b64 v[12:13], 9, v[12:13]
	v_lshl_or_b32 v12, v1, 2, v12
	v_lshl_add_u64 v[16:17], s[4:5], 0, v[12:13]
	global_store_dwordx4 v[16:17], v[84:87], off
	s_nop 1
	v_lshl_add_u64 v[4:5], s[6:7], 0, v[12:13]
	global_store_dwordx4 v[4:5], v[88:91], off
.Lsattn_5:
	s_or_b64 exec, exec, s[16:17]
	v_add_u32_e32 v12, 96, v112
	v_mad_u64_u32 v[18:19], s[12:13], v12, s96, v[0:1]
	v_cmp_lt_i32_e32 vcc, 3, v12
	s_waitcnt vmcnt(3)
	v_cvt_pk_bf16_f32 v16, v92, v93
	v_cvt_pk_bf16_f32 v17, v94, v95
	ds_write_b64 v18, v[16:17]
	s_waitcnt vmcnt(2)
	v_cvt_pk_bf16_f32 v16, v96, v97
	v_cvt_pk_bf16_f32 v17, v98, v99
	ds_write_b64 v18, v[16:17] offset:34848
	s_and_saveexec_b64 s[16:17], vcc
	s_cbranch_execz .Lsattn_6
	v_add_u32_e32 v2, -4, v12
	v_lshl_add_u64 v[12:13], s[10:11], 0, v[2:3]
	v_lshlrev_b64 v[12:13], 9, v[12:13]
	v_lshl_or_b32 v12, v1, 2, v12
	v_lshl_add_u64 v[16:17], s[4:5], 0, v[12:13]
	global_store_dwordx4 v[16:17], v[92:95], off
	s_nop 1
	v_lshl_add_u64 v[4:5], s[6:7], 0, v[12:13]
	global_store_dwordx4 v[4:5], v[96:99], off
.Lsattn_6:
	s_or_b64 exec, exec, s[16:17]
	v_add_u32_e32 v12, 112, v112
	v_mad_u64_u32 v[18:19], s[12:13], v12, s96, v[0:1]
	v_cmp_lt_i32_e32 vcc, 3, v12
	s_waitcnt vmcnt(1)
	v_cvt_pk_bf16_f32 v16, v100, v101
	v_cvt_pk_bf16_f32 v17, v102, v103
	ds_write_b64 v18, v[16:17]
	s_waitcnt vmcnt(0)
	v_cvt_pk_bf16_f32 v16, v104, v105
	v_cvt_pk_bf16_f32 v17, v106, v107
	ds_write_b64 v18, v[16:17] offset:34848
	s_and_saveexec_b64 s[16:17], vcc
	s_cbranch_execz .LBB0_640
	v_add_u32_e32 v2, -4, v12
	v_lshl_add_u64 v[12:13], s[10:11], 0, v[2:3]
	v_lshlrev_b64 v[12:13], 9, v[12:13]
	v_lshl_or_b32 v12, v1, 2, v12
	v_lshl_add_u64 v[16:17], s[4:5], 0, v[12:13]
	global_store_dwordx4 v[16:17], v[100:103], off
	s_nop 1
	v_lshl_add_u64 v[4:5], s[6:7], 0, v[12:13]
	global_store_dwordx4 v[4:5], v[104:107], off
